# in-projection plain epilogue: per-row rowss loads hoisted to the epilogue head (13 serialized load+store drains removed per tile)
# speedup vs baseline: 1.0132x; 1.0021x over previous
;     __device__ __forceinline__ void operator()(const f32x4 (&acc)[2][2][4][2], const Unit& u, int wr, int wc, int fr, int fq) const {
;     ...
;         if (pn < 6) {
; #pragma unroll
;             for (int bj = 0; bj < 2; ++bj) {
;                 size_t off; int pitch, c0;
;                 if (pn < 3) { off = (size_t)pn * QM * 256; pitch = 256; c0 = bj * 128; }
;                 else if (pn == 3) { off = OFF_QB; pitch = 384; c0 = bj * 128; }
;                 else if (pn == 4) { if (bj == 0) { off = OFF_QB; pitch = 384; c0 = 256; } else { off = OFF_KB; pitch = 128; c0 = 0; } }
;                 else { off = bj == 0 ? OFF_VB : OFF_VC; pitch = 128; c0 = 0; }
;                 bf16_t* base = qkv + off + c0 + wc * 32 + 8 * fqo;
;                 const f32x4 bz0 = *(const f32x4*)(bp + bj * HALF), bz1 = *(const f32x4*)(bp + bj * HALF + 4);
;                 const float qsc = (pn == 0 || pn == 3 || (pn == 4 && bj == 0)) ? 0.125f * 1.4426950408889634f : 1.0f;
;                 const bool isk = (pn == 1) || (pn == 4 && bj == 1);
;                 float kmx = 0.f;
; #pragma unroll
;                 for (int ai = 0; ai < 2; ++ai)
; #pragma unroll
;                     for (int m = 0; m < 4; ++m) {
;                         const int row = row0 + ai * HALF + m * 16;
;                         const float rv = rsqrtf(rowss[row] * (1.0f / 1024.0f) + 1e-6f);
;                         const f32x4 v0 = (acc[ai][bj][m][0] * rv + bz0) * qsc, v1 = (acc[ai][bj][m][1] * rv + bz1) * qsc;
;                         if (isk) { float s2 = (v0[0] * v0[0] + v0[1] * v0[1]) + (v0[2] * v0[2] + v0[3] * v0[3]) + (v1[0] * v1[0] + v1[1] * v1[1]) + (v1[2] * v1[2] + v1[3] * v1[3]);
;                             s2 += __shfl_xor(s2, 16); s2 += __shfl_xor(s2, 32); kmx = fmaxf(kmx, s2); }
;                         u32x4 w; w.x = pk_bf16(v0[0], v0[1]); w.y = pk_bf16(v0[2], v0[3]); w.z = pk_bf16(v1[0], v1[1]); w.w = pk_bf16(v1[2], v1[3]);
;                         *(u32x4*)(base + (size_t)row * pitch) = w;
;                     }
;                 if (isk) { kmx = fmaxf(kmx, __shfl_xor(kmx, 1)); kmx = fmaxf(kmx, __shfl_xor(kmx, 2)); kmx = fmaxf(kmx, __shfl_xor(kmx, 4)); kmx = fmaxf(kmx, __shfl_xor(kmx, 8));
;                     if (fr == 0 && fqo == 0) { const int grp = pn == 1 ? 0 : 1; const int head = pn == 1 ? bj * 2 + (wc >> 1) : (wc >> 1);
.LBB0_277:
	v_lshl_add_u64 v[138:139], v[162:163], 2, s[12:13]
	global_load_dword v141, v[138:139], off
	global_load_dword v188, v[138:139], off offset:64
	global_load_dword v189, v[138:139], off offset:128
	global_load_dword v190, v[138:139], off offset:192
	global_load_dword v191, v[138:139], off offset:512
	global_load_dword v192, v[138:139], off offset:576
	global_load_dword v193, v[138:139], off offset:640
	global_load_dword v194, v[138:139], off offset:704
	global_load_dword v195, v[138:139], off offset:128
	global_load_dword v196, v[138:139], off offset:192
	global_load_dword v197, v[138:139], off offset:512
	global_load_dword v198, v[138:139], off offset:576
	global_load_dword v199, v[138:139], off offset:640
	global_load_dword v200, v[138:139], off offset:704
	s_cmp_eq_u32 s66, 1
	s_cselect_b64 s[68:69], -1, 0
	s_cmp_lg_u32 s66, 1
	s_waitcnt vmcnt(0)
	v_fmamk_f32 v141, v141, 0x3a800000, v227
	v_mul_f32_e32 v159, 0x4b800000, v141
	v_cmp_gt_f32_e32 vcc, s36, v141
	s_nop 1
	v_cndmask_b32_e32 v141, v141, v159, vcc
	v_rsq_f32_e32 v141, v141
	s_nop 0
	v_mul_f32_e32 v159, 0x45800000, v141
	v_cndmask_b32_e32 v168, v141, v159, vcc
	v_pk_fma_f32 v[170:171], v[124:125], v[168:169], v[134:135] op_sel_hi:[1,0,1]
	v_pk_fma_f32 v[124:125], v[126:127], v[168:169], v[136:137] op_sel_hi:[1,0,1]
	v_pk_fma_f32 v[120:121], v[120:121], v[168:169], v[130:131] op_sel_hi:[1,0,1]
	v_pk_fma_f32 v[122:123], v[122:123], v[168:169], v[132:133] op_sel_hi:[1,0,1]
	v_pk_mul_f32 v[124:125], v[140:141], v[124:125] op_sel_hi:[0,1]
	v_pk_mul_f32 v[168:169], v[140:141], v[170:171] op_sel_hi:[0,1]
	v_pk_mul_f32 v[122:123], v[140:141], v[122:123] op_sel_hi:[0,1]
	v_pk_mul_f32 v[126:127], v[140:141], v[120:121] op_sel_hi:[0,1]
	v_mov_b32_e32 v159, 0
	s_cbranch_scc1 .LBB0_279
	v_pk_mul_f32 v[120:121], v[124:125], v[124:125]
	v_pk_mul_f32 v[170:171], v[168:169], v[168:169]
	v_and_b32_e32 v141, 64, v230
	v_pk_mov_b32 v[172:173], v[170:171], v[120:121] op_sel:[1,0]
	v_mov_b32_e32 v171, v121
	v_pk_add_f32 v[120:121], v[172:173], v[170:171]
	v_pk_mul_f32 v[170:171], v[122:123], v[122:123]
	v_pk_mul_f32 v[172:173], v[126:127], v[126:127]
	v_mov_b32_e32 v186, v170
	v_mov_b32_e32 v187, v172
	v_mov_b32_e32 v172, v171
	v_add_f32_e32 v120, v120, v121
	v_xor_b32_e32 v121, 16, v230
	v_add_u32_e32 v141, 64, v141
	v_pk_add_f32 v[170:171], v[186:187], v[172:173]
	v_cmp_lt_i32_e32 vcc, v121, v141
	v_add_f32_e32 v120, v171, v120
	v_add_f32_e32 v120, v170, v120
	v_cndmask_b32_e32 v121, v230, v121, vcc
	v_lshlrev_b32_e32 v121, 2, v121
	ds_bpermute_b32 v121, v121, v120
	s_waitcnt lgkmcnt(0)
	v_add_f32_e32 v120, v120, v121
	v_xor_b32_e32 v121, 32, v230
	v_cmp_lt_i32_e32 vcc, v121, v141
	s_nop 1
	v_cndmask_b32_e32 v121, v230, v121, vcc
	v_lshlrev_b32_e32 v121, 2, v121
	ds_bpermute_b32 v121, v121, v120
	s_waitcnt lgkmcnt(0)
	v_add_f32_e32 v120, v120, v121
	v_max_f32_e32 v159, 0, v120
.LBB0_279:
	s_lshl_b64 s[4:5], s[42:43], 1
	s_add_u32 s1, s2, s4
	s_addc_u32 s4, s3, s5
	s_lshl_b32 s0, s0, 1
	s_add_u32 s0, s1, s0
	s_addc_u32 s1, s4, 0
	s_lshl_b32 s59, s91, 1
	s_add_u32 s0, s0, s59
	s_addc_u32 s1, s1, 0
	v_lshl_add_u64 v[120:121], v[164:165], 1, s[0:1]
	v_cvt_pk_bf16_f32 v171, v122, v123
	v_mad_i64_i32 v[122:123], s[0:1], s74, v162, 0
	v_cvt_pk_bf16_f32 v168, v168, v169
	v_cvt_pk_bf16_f32 v169, v124, v125
	v_cvt_pk_bf16_f32 v170, v126, v127
	v_lshl_add_u64 v[122:123], v[122:123], 1, v[120:121]
	global_store_dwordx4 v[122:123], v[168:171], off
	s_nop 0
	v_mov_b32_e32 v141, v140
	v_mov_b32_e32 v122, v140
	v_mov_b32_e32 v123, v140
	s_andn2_b64 vcc, exec, s[68:69]
	v_fmamk_f32 v124, v188, 0x3a800000, v227
	v_mul_f32_e32 v125, 0x4b800000, v124
	v_cmp_gt_f32_e64 s[0:1], s36, v124
	s_nop 1
	v_cndmask_b32_e64 v124, v124, v125, s[0:1]
	v_rsq_f32_e32 v124, v124
	v_cndmask_b32_e64 v125, 0, 1, s[68:69]
	v_cmp_ne_u32_e64 s[42:43], 1, v125
	v_mul_f32_e32 v125, 0x45800000, v124
	v_cndmask_b32_e64 v124, v124, v125, s[0:1]
	v_pk_fma_f32 v[116:117], v[116:117], v[124:125], v[134:135] op_sel_hi:[1,0,1]
	v_pk_fma_f32 v[118:119], v[118:119], v[124:125], v[136:137] op_sel_hi:[1,0,1]
	v_pk_fma_f32 v[126:127], v[112:113], v[124:125], v[130:131] op_sel_hi:[1,0,1]
	v_pk_fma_f32 v[112:113], v[114:115], v[124:125], v[132:133] op_sel_hi:[1,0,1]
	v_pk_mul_f32 v[114:115], v[122:123], v[118:119]
	v_pk_mul_f32 v[118:119], v[140:141], v[116:117]
	v_pk_mul_f32 v[112:113], v[122:123], v[112:113]
	v_pk_mul_f32 v[116:117], v[140:141], v[126:127]
	s_cbranch_vccnz .LBB0_281
	v_pk_mul_f32 v[124:125], v[114:115], v[114:115]
	v_pk_mul_f32 v[126:127], v[118:119], v[118:119]
	s_nop 0
	v_pk_mov_b32 v[168:169], v[126:127], v[124:125] op_sel:[1,0]
	v_mov_b32_e32 v127, v125
	v_pk_add_f32 v[124:125], v[168:169], v[126:127]
	v_pk_mul_f32 v[126:127], v[112:113], v[112:113]
	v_pk_mul_f32 v[168:169], v[116:117], v[116:117]
	v_mov_b32_e32 v170, v126
	v_mov_b32_e32 v171, v168
	v_mov_b32_e32 v168, v127
	v_pk_add_f32 v[126:127], v[170:171], v[168:169]
	v_add_f32_e32 v124, v124, v125
	v_add_f32_e32 v124, v127, v124
	v_add_f32_e32 v124, v126, v124
	v_and_b32_e32 v126, 64, v230
	v_xor_b32_e32 v125, 16, v230
	v_add_u32_e32 v126, 64, v126
	v_cmp_lt_i32_e32 vcc, v125, v126
	s_nop 1
	v_cndmask_b32_e32 v125, v230, v125, vcc
	v_lshlrev_b32_e32 v125, 2, v125
	ds_bpermute_b32 v125, v125, v124
	s_waitcnt lgkmcnt(0)
	v_add_f32_e32 v124, v124, v125
	v_xor_b32_e32 v125, 32, v230
	v_cmp_lt_i32_e32 vcc, v125, v126
	s_nop 1
	v_cndmask_b32_e32 v125, v230, v125, vcc
	v_lshlrev_b32_e32 v125, 2, v125
	ds_bpermute_b32 v125, v125, v124
	s_waitcnt lgkmcnt(0)
	v_add_f32_e32 v124, v124, v125
	v_max_f32_e32 v125, v159, v159
	v_max_f32_e32 v159, v125, v124
; __device__ __forceinline__ unsigned pk_bf16(float lo, float hi) { f32x2 v = {lo, hi}; bf16x2_t b = __builtin_convertvector(v, bf16x2_t); return __builtin_bit_cast(unsigned, b); }
;     __device__ __forceinline__ void operator()(const f32x4 (&acc)[2][2][4][2], const Unit& u, int wr, int wc, int fr, int fq) const {
;     ...
;                 for (int ai = 0; ai < 2; ++ai)
; #pragma unroll
;                     for (int m = 0; m < 4; ++m) {
;                         const int row = row0 + ai * HALF + m * 16;
;                         const float rv = rsqrtf(rowss[row] * (1.0f / 1024.0f) + 1e-6f);
;                         const f32x4 v0 = (acc[ai][bj][m][0] * rv + bz0) * qsc, v1 = (acc[ai][bj][m][1] * rv + bz1) * qsc;
;                         if (isk) { float s2 = (v0[0] * v0[0] + v0[1] * v0[1]) + (v0[2] * v0[2] + v0[3] * v0[3]) + (v1[0] * v1[0] + v1[1] * v1[1]) + (v1[2] * v1[2] + v1[3] * v1[3]);
;                             s2 += __shfl_xor(s2, 16); s2 += __shfl_xor(s2, 32); kmx = fmaxf(kmx, s2); }
;                         u32x4 w; w.x = pk_bf16(v0[0], v0[1]); w.y = pk_bf16(v0[2], v0[3]); w.z = pk_bf16(v1[0], v1[1]); w.w = pk_bf16(v1[2], v1[3]);
;                         *(u32x4*)(base + (size_t)row * pitch) = w;
;                     }
.LBB0_281:
	v_cvt_pk_bf16_f32 v127, v112, v113
	v_mad_i64_i32 v[112:113], s[0:1], s74, v243, 0
	v_cvt_pk_bf16_f32 v124, v118, v119
	v_cvt_pk_bf16_f32 v125, v114, v115
	v_cvt_pk_bf16_f32 v126, v116, v117
	v_lshl_add_u64 v[112:113], v[112:113], 1, v[120:121]
	global_store_dwordx4 v[112:113], v[124:127], off
	s_nop 0
	s_and_b64 vcc, exec, s[42:43]
	v_fmamk_f32 v112, v189, 0x3a800000, v227
	v_mul_f32_e32 v113, 0x4b800000, v112
	v_cmp_gt_f32_e64 s[0:1], s36, v112
	s_nop 1
	v_cndmask_b32_e64 v112, v112, v113, s[0:1]
	v_rsq_f32_e32 v112, v112
	s_nop 0
	v_mul_f32_e32 v113, 0x45800000, v112
	v_cndmask_b32_e64 v112, v112, v113, s[0:1]
	v_pk_fma_f32 v[108:109], v[108:109], v[112:113], v[134:135] op_sel_hi:[1,0,1]
	v_pk_fma_f32 v[110:111], v[110:111], v[112:113], v[136:137] op_sel_hi:[1,0,1]
	v_pk_fma_f32 v[114:115], v[104:105], v[112:113], v[130:131] op_sel_hi:[1,0,1]
	v_pk_fma_f32 v[104:105], v[106:107], v[112:113], v[132:133] op_sel_hi:[1,0,1]
	v_pk_mul_f32 v[106:107], v[122:123], v[110:111]
	v_pk_mul_f32 v[110:111], v[140:141], v[108:109]
	v_pk_mul_f32 v[104:105], v[122:123], v[104:105]
	v_pk_mul_f32 v[108:109], v[140:141], v[114:115]
	s_cbranch_vccnz .LBB0_283
	v_pk_mul_f32 v[112:113], v[106:107], v[106:107]
	v_pk_mul_f32 v[114:115], v[110:111], v[110:111]
	s_nop 0
	v_pk_mov_b32 v[116:117], v[114:115], v[112:113] op_sel:[1,0]
	v_mov_b32_e32 v115, v113
	v_pk_add_f32 v[112:113], v[116:117], v[114:115]
	v_pk_mul_f32 v[114:115], v[104:105], v[104:105]
	v_pk_mul_f32 v[116:117], v[108:109], v[108:109]
	v_mov_b32_e32 v118, v114
	v_mov_b32_e32 v119, v116
	v_mov_b32_e32 v116, v115
	v_pk_add_f32 v[114:115], v[118:119], v[116:117]
	v_add_f32_e32 v112, v112, v113
	v_add_f32_e32 v112, v115, v112
	v_add_f32_e32 v112, v114, v112
	v_and_b32_e32 v114, 64, v230
	v_xor_b32_e32 v113, 16, v230
	v_add_u32_e32 v114, 64, v114
	v_cmp_lt_i32_e32 vcc, v113, v114
	s_nop 1
	v_cndmask_b32_e32 v113, v230, v113, vcc
	v_lshlrev_b32_e32 v113, 2, v113
	ds_bpermute_b32 v113, v113, v112
	s_waitcnt lgkmcnt(0)
	v_add_f32_e32 v112, v112, v113
	v_xor_b32_e32 v113, 32, v230
	v_cmp_lt_i32_e32 vcc, v113, v114
	s_nop 1
	v_cndmask_b32_e32 v113, v230, v113, vcc
	v_lshlrev_b32_e32 v113, 2, v113
	ds_bpermute_b32 v113, v113, v112
	s_waitcnt lgkmcnt(0)
	v_add_f32_e32 v112, v112, v113
	v_max_f32_e32 v113, v159, v159
	v_max_f32_e32 v159, v113, v112
.LBB0_283:
	v_cvt_pk_bf16_f32 v113, v104, v105
	v_mad_i64_i32 v[104:105], s[0:1], s74, v242, 0
	v_cvt_pk_bf16_f32 v110, v110, v111
	v_cvt_pk_bf16_f32 v111, v106, v107
	v_cvt_pk_bf16_f32 v112, v108, v109
	v_lshl_add_u64 v[104:105], v[104:105], 1, v[120:121]
	global_store_dwordx4 v[104:105], v[110:113], off
	s_nop 0
	s_and_b64 vcc, exec, s[42:43]
	v_fmamk_f32 v104, v190, 0x3a800000, v227
	v_mul_f32_e32 v105, 0x4b800000, v104
	v_cmp_gt_f32_e64 s[0:1], s36, v104
	s_nop 1
	v_cndmask_b32_e64 v104, v104, v105, s[0:1]
	v_rsq_f32_e32 v106, v104
	v_mov_b32_e32 v104, v140
	v_mov_b32_e32 v105, v140
	v_mul_f32_e32 v107, 0x45800000, v106
	v_cndmask_b32_e64 v106, v106, v107, s[0:1]
	v_pk_fma_f32 v[100:101], v[100:101], v[106:107], v[134:135] op_sel_hi:[1,0,1]
	v_pk_fma_f32 v[102:103], v[102:103], v[106:107], v[136:137] op_sel_hi:[1,0,1]
	v_pk_fma_f32 v[108:109], v[96:97], v[106:107], v[130:131] op_sel_hi:[1,0,1]
	v_pk_fma_f32 v[96:97], v[98:99], v[106:107], v[132:133] op_sel_hi:[1,0,1]
	v_pk_mul_f32 v[98:99], v[104:105], v[102:103]
	v_pk_mul_f32 v[102:103], v[140:141], v[100:101]
	v_pk_mul_f32 v[96:97], v[104:105], v[96:97]
	v_pk_mul_f32 v[100:101], v[140:141], v[108:109]
	s_cbranch_vccnz .LBB0_285
	v_pk_mul_f32 v[106:107], v[98:99], v[98:99]
	v_pk_mul_f32 v[108:109], v[102:103], v[102:103]
	s_nop 0
	v_pk_mov_b32 v[110:111], v[108:109], v[106:107] op_sel:[1,0]
	v_mov_b32_e32 v109, v107
	v_pk_add_f32 v[106:107], v[110:111], v[108:109]
	v_pk_mul_f32 v[108:109], v[96:97], v[96:97]
	v_pk_mul_f32 v[110:111], v[100:101], v[100:101]
	v_mov_b32_e32 v112, v108
	v_mov_b32_e32 v113, v110
	v_mov_b32_e32 v110, v109
	v_pk_add_f32 v[108:109], v[112:113], v[110:111]
	v_add_f32_e32 v106, v106, v107
	v_add_f32_e32 v106, v109, v106
	v_add_f32_e32 v106, v108, v106
	v_and_b32_e32 v108, 64, v230
	v_xor_b32_e32 v107, 16, v230
	v_add_u32_e32 v108, 64, v108
	v_cmp_lt_i32_e32 vcc, v107, v108
	s_nop 1
	v_cndmask_b32_e32 v107, v230, v107, vcc
	v_lshlrev_b32_e32 v107, 2, v107
	ds_bpermute_b32 v107, v107, v106
	s_waitcnt lgkmcnt(0)
	v_add_f32_e32 v106, v106, v107
	v_xor_b32_e32 v107, 32, v230
	v_cmp_lt_i32_e32 vcc, v107, v108
	s_nop 1
	v_cndmask_b32_e32 v107, v230, v107, vcc
	v_lshlrev_b32_e32 v107, 2, v107
	ds_bpermute_b32 v107, v107, v106
	s_waitcnt lgkmcnt(0)
	v_add_f32_e32 v106, v106, v107
	v_max_f32_e32 v107, v159, v159
	v_max_f32_e32 v159, v107, v106
; __device__ __forceinline__ unsigned pk_bf16(float lo, float hi) { f32x2 v = {lo, hi}; bf16x2_t b = __builtin_convertvector(v, bf16x2_t); return __builtin_bit_cast(unsigned, b); }
;     __device__ __forceinline__ void operator()(const f32x4 (&acc)[2][2][4][2], const Unit& u, int wr, int wc, int fr, int fq) const {
;     ...
;                 for (int ai = 0; ai < 2; ++ai)
; #pragma unroll
;                     for (int m = 0; m < 4; ++m) {
;                         const int row = row0 + ai * HALF + m * 16;
;                         const float rv = rsqrtf(rowss[row] * (1.0f / 1024.0f) + 1e-6f);
;                         const f32x4 v0 = (acc[ai][bj][m][0] * rv + bz0) * qsc, v1 = (acc[ai][bj][m][1] * rv + bz1) * qsc;
;                         if (isk) { float s2 = (v0[0] * v0[0] + v0[1] * v0[1]) + (v0[2] * v0[2] + v0[3] * v0[3]) + (v1[0] * v1[0] + v1[1] * v1[1]) + (v1[2] * v1[2] + v1[3] * v1[3]);
;                             s2 += __shfl_xor(s2, 16); s2 += __shfl_xor(s2, 32); kmx = fmaxf(kmx, s2); }
;                         u32x4 w; w.x = pk_bf16(v0[0], v0[1]); w.y = pk_bf16(v0[2], v0[3]); w.z = pk_bf16(v1[0], v1[1]); w.w = pk_bf16(v1[2], v1[3]);
;                         *(u32x4*)(base + (size_t)row * pitch) = w;
;                     }
.LBB0_285:
	v_cvt_pk_bf16_f32 v109, v96, v97
	v_mad_i64_i32 v[96:97], s[0:1], s74, v241, 0
	v_cvt_pk_bf16_f32 v106, v102, v103
	v_cvt_pk_bf16_f32 v107, v98, v99
	v_cvt_pk_bf16_f32 v108, v100, v101
	v_lshl_add_u64 v[96:97], v[96:97], 1, v[120:121]
	global_store_dwordx4 v[96:97], v[106:109], off
	s_nop 0
	s_and_b64 vcc, exec, s[42:43]
	v_fmamk_f32 v96, v191, 0x3a800000, v227
	v_mul_f32_e32 v97, 0x4b800000, v96
	v_cmp_gt_f32_e64 s[0:1], s36, v96
	s_nop 1
	v_cndmask_b32_e64 v96, v96, v97, s[0:1]
	v_rsq_f32_e32 v96, v96
	s_nop 0
	v_mul_f32_e32 v97, 0x45800000, v96
	v_cndmask_b32_e64 v96, v96, v97, s[0:1]
	v_pk_fma_f32 v[92:93], v[92:93], v[96:97], v[134:135] op_sel_hi:[1,0,1]
	v_pk_fma_f32 v[94:95], v[94:95], v[96:97], v[136:137] op_sel_hi:[1,0,1]
	v_pk_fma_f32 v[98:99], v[88:89], v[96:97], v[130:131] op_sel_hi:[1,0,1]
	v_pk_fma_f32 v[88:89], v[90:91], v[96:97], v[132:133] op_sel_hi:[1,0,1]
	v_pk_mul_f32 v[90:91], v[104:105], v[94:95]
	v_pk_mul_f32 v[94:95], v[140:141], v[92:93]
	v_pk_mul_f32 v[88:89], v[104:105], v[88:89]
	v_pk_mul_f32 v[92:93], v[140:141], v[98:99]
	s_cbranch_vccnz .LBB0_287
	v_pk_mul_f32 v[96:97], v[90:91], v[90:91]
	v_pk_mul_f32 v[98:99], v[94:95], v[94:95]
	s_nop 0
	v_pk_mov_b32 v[100:101], v[98:99], v[96:97] op_sel:[1,0]
	v_mov_b32_e32 v99, v97
	v_pk_add_f32 v[96:97], v[100:101], v[98:99]
	v_pk_mul_f32 v[98:99], v[88:89], v[88:89]
	v_pk_mul_f32 v[100:101], v[92:93], v[92:93]
	v_mov_b32_e32 v102, v98
	v_mov_b32_e32 v103, v100
	v_mov_b32_e32 v100, v99
	v_pk_add_f32 v[98:99], v[102:103], v[100:101]
	v_add_f32_e32 v96, v96, v97
	v_add_f32_e32 v96, v99, v96
	v_add_f32_e32 v96, v98, v96
	v_and_b32_e32 v98, 64, v230
	v_xor_b32_e32 v97, 16, v230
	v_add_u32_e32 v98, 64, v98
	v_cmp_lt_i32_e32 vcc, v97, v98
	s_nop 1
	v_cndmask_b32_e32 v97, v230, v97, vcc
	v_lshlrev_b32_e32 v97, 2, v97
	ds_bpermute_b32 v97, v97, v96
	s_waitcnt lgkmcnt(0)
	v_add_f32_e32 v96, v96, v97
	v_xor_b32_e32 v97, 32, v230
	v_cmp_lt_i32_e32 vcc, v97, v98
	s_nop 1
	v_cndmask_b32_e32 v97, v230, v97, vcc
	v_lshlrev_b32_e32 v97, 2, v97
	ds_bpermute_b32 v97, v97, v96
	s_waitcnt lgkmcnt(0)
	v_add_f32_e32 v96, v96, v97
	v_max_f32_e32 v97, v159, v159
	v_max_f32_e32 v159, v97, v96
.LBB0_287:
	v_add_u32_e32 v96, 0x80, v162
	v_cvt_pk_bf16_f32 v101, v88, v89
	v_mad_i64_i32 v[88:89], s[0:1], s74, v96, 0
	v_cvt_pk_bf16_f32 v98, v94, v95
	v_cvt_pk_bf16_f32 v99, v90, v91
	v_cvt_pk_bf16_f32 v100, v92, v93
	v_lshl_add_u64 v[88:89], v[88:89], 1, v[120:121]
	global_store_dwordx4 v[88:89], v[98:101], off
	s_nop 0
	s_and_b64 vcc, exec, s[42:43]
	v_fmamk_f32 v88, v192, 0x3a800000, v227
	v_mul_f32_e32 v89, 0x4b800000, v88
	v_cmp_gt_f32_e64 s[0:1], s36, v88
	s_nop 1
	v_cndmask_b32_e64 v88, v88, v89, s[0:1]
	v_rsq_f32_e32 v90, v88
	v_mov_b32_e32 v88, v140
	v_mov_b32_e32 v89, v140
	v_mul_f32_e32 v91, 0x45800000, v90
	v_cndmask_b32_e64 v90, v90, v91, s[0:1]
	v_pk_fma_f32 v[84:85], v[84:85], v[90:91], v[134:135] op_sel_hi:[1,0,1]
	v_pk_fma_f32 v[86:87], v[86:87], v[90:91], v[136:137] op_sel_hi:[1,0,1]
	v_pk_fma_f32 v[92:93], v[80:81], v[90:91], v[130:131] op_sel_hi:[1,0,1]
	v_pk_fma_f32 v[80:81], v[82:83], v[90:91], v[132:133] op_sel_hi:[1,0,1]
	v_pk_mul_f32 v[82:83], v[88:89], v[86:87]
	v_pk_mul_f32 v[86:87], v[140:141], v[84:85]
	v_pk_mul_f32 v[80:81], v[88:89], v[80:81]
	v_pk_mul_f32 v[84:85], v[140:141], v[92:93]
	s_cbranch_vccnz .LBB0_289
	v_pk_mul_f32 v[90:91], v[82:83], v[82:83]
	v_pk_mul_f32 v[92:93], v[86:87], v[86:87]
	s_nop 0
	v_pk_mov_b32 v[94:95], v[92:93], v[90:91] op_sel:[1,0]
	v_mov_b32_e32 v93, v91
	v_pk_add_f32 v[90:91], v[94:95], v[92:93]
	v_pk_mul_f32 v[92:93], v[80:81], v[80:81]
	v_pk_mul_f32 v[94:95], v[84:85], v[84:85]
	v_mov_b32_e32 v98, v92
	v_mov_b32_e32 v99, v94
	v_mov_b32_e32 v94, v93
	v_pk_add_f32 v[92:93], v[98:99], v[94:95]
	v_add_f32_e32 v90, v90, v91
	v_add_f32_e32 v90, v93, v90
	v_add_f32_e32 v90, v92, v90
	v_and_b32_e32 v92, 64, v230
	v_xor_b32_e32 v91, 16, v230
	v_add_u32_e32 v92, 64, v92
	v_cmp_lt_i32_e32 vcc, v91, v92
	s_nop 1
	v_cndmask_b32_e32 v91, v230, v91, vcc
	v_lshlrev_b32_e32 v91, 2, v91
	ds_bpermute_b32 v91, v91, v90
	s_waitcnt lgkmcnt(0)
	v_add_f32_e32 v90, v90, v91
	v_xor_b32_e32 v91, 32, v230
	v_cmp_lt_i32_e32 vcc, v91, v92
	s_nop 1
	v_cndmask_b32_e32 v91, v230, v91, vcc
	v_lshlrev_b32_e32 v91, 2, v91
	ds_bpermute_b32 v91, v91, v90
	s_waitcnt lgkmcnt(0)
	v_add_f32_e32 v90, v90, v91
	v_max_f32_e32 v91, v159, v159
	v_max_f32_e32 v159, v91, v90
; __device__ __forceinline__ unsigned pk_bf16(float lo, float hi) { f32x2 v = {lo, hi}; bf16x2_t b = __builtin_convertvector(v, bf16x2_t); return __builtin_bit_cast(unsigned, b); }
;     __device__ __forceinline__ void operator()(const f32x4 (&acc)[2][2][4][2], const Unit& u, int wr, int wc, int fr, int fq) const {
;     ...
;                 for (int ai = 0; ai < 2; ++ai)
; #pragma unroll
;                     for (int m = 0; m < 4; ++m) {
;                         const int row = row0 + ai * HALF + m * 16;
;                         const float rv = rsqrtf(rowss[row] * (1.0f / 1024.0f) + 1e-6f);
;                         const f32x4 v0 = (acc[ai][bj][m][0] * rv + bz0) * qsc, v1 = (acc[ai][bj][m][1] * rv + bz1) * qsc;
;                         if (isk) { float s2 = (v0[0] * v0[0] + v0[1] * v0[1]) + (v0[2] * v0[2] + v0[3] * v0[3]) + (v1[0] * v1[0] + v1[1] * v1[1]) + (v1[2] * v1[2] + v1[3] * v1[3]);
;                             s2 += __shfl_xor(s2, 16); s2 += __shfl_xor(s2, 32); kmx = fmaxf(kmx, s2); }
;                         u32x4 w; w.x = pk_bf16(v0[0], v0[1]); w.y = pk_bf16(v0[2], v0[3]); w.z = pk_bf16(v1[0], v1[1]); w.w = pk_bf16(v1[2], v1[3]);
;                         *(u32x4*)(base + (size_t)row * pitch) = w;
;                     }
.LBB0_289:
	v_add_u32_e32 v90, 0x90, v162
	v_cvt_pk_bf16_f32 v95, v80, v81
	v_mad_i64_i32 v[80:81], s[0:1], s74, v90, 0
	v_cvt_pk_bf16_f32 v92, v86, v87
	v_cvt_pk_bf16_f32 v93, v82, v83
	v_cvt_pk_bf16_f32 v94, v84, v85
	v_lshl_add_u64 v[80:81], v[80:81], 1, v[120:121]
	global_store_dwordx4 v[80:81], v[92:95], off
	s_nop 0
	s_and_b64 vcc, exec, s[42:43]
	v_fmamk_f32 v80, v193, 0x3a800000, v227
	v_mul_f32_e32 v81, 0x4b800000, v80
	v_cmp_gt_f32_e64 s[0:1], s36, v80
	s_nop 1
	v_cndmask_b32_e64 v80, v80, v81, s[0:1]
	v_rsq_f32_e32 v80, v80
	s_nop 0
	v_mul_f32_e32 v81, 0x45800000, v80
	v_cndmask_b32_e64 v80, v80, v81, s[0:1]
	v_pk_fma_f32 v[76:77], v[76:77], v[80:81], v[134:135] op_sel_hi:[1,0,1]
	v_pk_fma_f32 v[78:79], v[78:79], v[80:81], v[136:137] op_sel_hi:[1,0,1]
	v_pk_fma_f32 v[82:83], v[72:73], v[80:81], v[130:131] op_sel_hi:[1,0,1]
	v_pk_fma_f32 v[72:73], v[74:75], v[80:81], v[132:133] op_sel_hi:[1,0,1]
	v_pk_mul_f32 v[74:75], v[88:89], v[78:79]
	v_pk_mul_f32 v[78:79], v[140:141], v[76:77]
	v_pk_mul_f32 v[72:73], v[88:89], v[72:73]
	v_pk_mul_f32 v[76:77], v[140:141], v[82:83]
	s_cbranch_vccnz .LBB0_291
	v_pk_mul_f32 v[80:81], v[74:75], v[74:75]
	v_pk_mul_f32 v[82:83], v[78:79], v[78:79]
	s_nop 0
	v_pk_mov_b32 v[84:85], v[82:83], v[80:81] op_sel:[1,0]
	v_mov_b32_e32 v83, v81
	v_pk_add_f32 v[80:81], v[84:85], v[82:83]
	v_pk_mul_f32 v[82:83], v[72:73], v[72:73]
	v_pk_mul_f32 v[84:85], v[76:77], v[76:77]
	v_mov_b32_e32 v86, v82
	v_mov_b32_e32 v87, v84
	v_mov_b32_e32 v84, v83
	v_pk_add_f32 v[82:83], v[86:87], v[84:85]
	v_add_f32_e32 v80, v80, v81
	v_add_f32_e32 v80, v83, v80
	v_add_f32_e32 v80, v82, v80
	v_and_b32_e32 v82, 64, v230
	v_xor_b32_e32 v81, 16, v230
	v_add_u32_e32 v82, 64, v82
	v_cmp_lt_i32_e32 vcc, v81, v82
	s_nop 1
	v_cndmask_b32_e32 v81, v230, v81, vcc
	v_lshlrev_b32_e32 v81, 2, v81
	ds_bpermute_b32 v81, v81, v80
	s_waitcnt lgkmcnt(0)
	v_add_f32_e32 v80, v80, v81
	v_xor_b32_e32 v81, 32, v230
	v_cmp_lt_i32_e32 vcc, v81, v82
	s_nop 1
	v_cndmask_b32_e32 v81, v230, v81, vcc
	v_lshlrev_b32_e32 v81, 2, v81
	ds_bpermute_b32 v81, v81, v80
	s_waitcnt lgkmcnt(0)
	v_add_f32_e32 v80, v80, v81
	v_max_f32_e32 v81, v159, v159
	v_max_f32_e32 v159, v81, v80
.LBB0_291:
	v_add_u32_e32 v80, 0xa0, v162
	v_cvt_pk_bf16_f32 v85, v72, v73
	v_mad_i64_i32 v[72:73], s[0:1], s74, v80, 0
	v_cvt_pk_bf16_f32 v82, v78, v79
	v_cvt_pk_bf16_f32 v83, v74, v75
	v_cvt_pk_bf16_f32 v84, v76, v77
	v_lshl_add_u64 v[72:73], v[72:73], 1, v[120:121]
	global_store_dwordx4 v[72:73], v[82:85], off
	s_nop 0
	s_and_b64 vcc, exec, s[42:43]
	v_fmamk_f32 v72, v194, 0x3a800000, v227
	v_mul_f32_e32 v73, 0x4b800000, v72
	v_cmp_gt_f32_e64 s[0:1], s36, v72
	s_nop 1
	v_cndmask_b32_e64 v72, v72, v73, s[0:1]
	v_rsq_f32_e32 v74, v72
	v_mov_b32_e32 v72, v140
	v_mov_b32_e32 v73, v140
	v_mul_f32_e32 v75, 0x45800000, v74
	v_cndmask_b32_e64 v74, v74, v75, s[0:1]
	v_pk_fma_f32 v[68:69], v[68:69], v[74:75], v[134:135] op_sel_hi:[1,0,1]
	v_pk_fma_f32 v[70:71], v[70:71], v[74:75], v[136:137] op_sel_hi:[1,0,1]
	v_pk_fma_f32 v[76:77], v[64:65], v[74:75], v[130:131] op_sel_hi:[1,0,1]
	v_pk_fma_f32 v[64:65], v[66:67], v[74:75], v[132:133] op_sel_hi:[1,0,1]
	v_pk_mul_f32 v[66:67], v[72:73], v[70:71]
	v_pk_mul_f32 v[70:71], v[140:141], v[68:69]
	v_pk_mul_f32 v[64:65], v[72:73], v[64:65]
	v_pk_mul_f32 v[68:69], v[140:141], v[76:77]
	s_cbranch_vccnz .LBB0_293
	v_pk_mul_f32 v[72:73], v[66:67], v[66:67]
	v_pk_mul_f32 v[74:75], v[70:71], v[70:71]
	s_nop 0
	v_pk_mov_b32 v[76:77], v[74:75], v[72:73] op_sel:[1,0]
	v_mov_b32_e32 v75, v73
	v_pk_add_f32 v[72:73], v[76:77], v[74:75]
	v_pk_mul_f32 v[74:75], v[64:65], v[64:65]
	v_pk_mul_f32 v[76:77], v[68:69], v[68:69]
	v_mov_b32_e32 v78, v74
	v_mov_b32_e32 v79, v76
	v_mov_b32_e32 v76, v75
	v_pk_add_f32 v[74:75], v[78:79], v[76:77]
	v_add_f32_e32 v72, v72, v73
	v_add_f32_e32 v72, v75, v72
	v_add_f32_e32 v72, v74, v72
	v_and_b32_e32 v74, 64, v230
	v_xor_b32_e32 v73, 16, v230
	v_add_u32_e32 v74, 64, v74
	v_cmp_lt_i32_e32 vcc, v73, v74
	s_nop 1
	v_cndmask_b32_e32 v73, v230, v73, vcc
	v_lshlrev_b32_e32 v73, 2, v73
	ds_bpermute_b32 v73, v73, v72
	s_waitcnt lgkmcnt(0)
	v_add_f32_e32 v72, v72, v73
	v_xor_b32_e32 v73, 32, v230
	v_cmp_lt_i32_e32 vcc, v73, v74
	s_nop 1
	v_cndmask_b32_e32 v73, v230, v73, vcc
	v_lshlrev_b32_e32 v73, 2, v73
	ds_bpermute_b32 v73, v73, v72
	s_waitcnt lgkmcnt(0)
	v_add_f32_e32 v72, v72, v73
	v_max_f32_e32 v73, v159, v159
	v_max_f32_e32 v159, v73, v72

; __device__ __forceinline__ unsigned pk_bf16(float lo, float hi) { f32x2 v = {lo, hi}; bf16x2_t b = __builtin_convertvector(v, bf16x2_t); return __builtin_bit_cast(unsigned, b); }
;     __device__ __forceinline__ void operator()(const f32x4 (&acc)[2][2][4][2], const Unit& u, int wr, int wc, int fr, int fq) const {
;     ...
;                 for (int ai = 0; ai < 2; ++ai)
; #pragma unroll
;                     for (int m = 0; m < 4; ++m) {
;                         const int row = row0 + ai * HALF + m * 16;
;                         const float rv = rsqrtf(rowss[row] * (1.0f / 1024.0f) + 1e-6f);
;                         const f32x4 v0 = (acc[ai][bj][m][0] * rv + bz0) * qsc, v1 = (acc[ai][bj][m][1] * rv + bz1) * qsc;
;                         if (isk) { float s2 = (v0[0] * v0[0] + v0[1] * v0[1]) + (v0[2] * v0[2] + v0[3] * v0[3]) + (v1[0] * v1[0] + v1[1] * v1[1]) + (v1[2] * v1[2] + v1[3] * v1[3]);
;                             s2 += __shfl_xor(s2, 16); s2 += __shfl_xor(s2, 32); kmx = fmaxf(kmx, s2); }
;                         u32x4 w; w.x = pk_bf16(v0[0], v0[1]); w.y = pk_bf16(v0[2], v0[3]); w.z = pk_bf16(v1[0], v1[1]); w.w = pk_bf16(v1[2], v1[3]);
;                         *(u32x4*)(base + (size_t)row * pitch) = w;
.LBB0_321:
	v_cvt_pk_bf16_f32 v61, v48, v49
	v_mad_i64_i32 v[48:49], s[0:1], s42, v243, 0
	v_cvt_pk_bf16_f32 v58, v54, v55
	v_cvt_pk_bf16_f32 v59, v52, v53
	v_cvt_pk_bf16_f32 v60, v50, v51
	v_lshl_add_u64 v[48:49], v[48:49], 1, v[56:57]
	global_store_dwordx4 v[48:49], v[58:61], off
	s_nop 0
	s_cmp_lt_i32 s66, 4
	v_fmamk_f32 v48, v195, 0x3a800000, v227
	v_cmp_gt_f32_e64 s[0:1], s36, v48
	s_cbranch_scc1 .LBB0_323
	s_cmp_eq_u32 s66, 4
	s_cselect_b64 s[4:5], -1, 0
	s_cbranch_execz .LBB0_324
	s_branch .LBB0_325

; __device__ __forceinline__ unsigned pk_bf16(float lo, float hi) { f32x2 v = {lo, hi}; bf16x2_t b = __builtin_convertvector(v, bf16x2_t); return __builtin_bit_cast(unsigned, b); }
;     __device__ __forceinline__ void operator()(const f32x4 (&acc)[2][2][4][2], const Unit& u, int wr, int wc, int fr, int fq) const {
;     ...
;                 for (int ai = 0; ai < 2; ++ai)
; #pragma unroll
;                     for (int m = 0; m < 4; ++m) {
;                         const int row = row0 + ai * HALF + m * 16;
;                         const float rv = rsqrtf(rowss[row] * (1.0f / 1024.0f) + 1e-6f);
;                         const f32x4 v0 = (acc[ai][bj][m][0] * rv + bz0) * qsc, v1 = (acc[ai][bj][m][1] * rv + bz1) * qsc;
;                         if (isk) { float s2 = (v0[0] * v0[0] + v0[1] * v0[1]) + (v0[2] * v0[2] + v0[3] * v0[3]) + (v1[0] * v1[0] + v1[1] * v1[1]) + (v1[2] * v1[2] + v1[3] * v1[3]);
;                             s2 += __shfl_xor(s2, 16); s2 += __shfl_xor(s2, 32); kmx = fmaxf(kmx, s2); }
;                         u32x4 w; w.x = pk_bf16(v0[0], v0[1]); w.y = pk_bf16(v0[2], v0[3]); w.z = pk_bf16(v1[0], v1[1]); w.w = pk_bf16(v1[2], v1[3]);
;                         *(u32x4*)(base + (size_t)row * pitch) = w;
.LBB0_327:
	v_cvt_pk_bf16_f32 v49, v40, v41
	v_mad_i64_i32 v[40:41], s[0:1], s42, v242, 0
	v_cvt_pk_bf16_f32 v46, v46, v47
	v_cvt_pk_bf16_f32 v47, v44, v45
	v_cvt_pk_bf16_f32 v48, v42, v43
	v_lshl_add_u64 v[40:41], v[40:41], 1, v[56:57]
	global_store_dwordx4 v[40:41], v[46:49], off
	s_nop 0
	s_cmp_lt_i32 s66, 4
	v_fmamk_f32 v40, v196, 0x3a800000, v227
	v_cmp_gt_f32_e64 s[0:1], s36, v40
	s_cbranch_scc1 .LBB0_329
	s_cmp_eq_u32 s66, 4
	s_cselect_b64 s[4:5], -1, 0
	s_cbranch_execz .LBB0_330
	s_branch .LBB0_331

; __device__ __forceinline__ unsigned pk_bf16(float lo, float hi) { f32x2 v = {lo, hi}; bf16x2_t b = __builtin_convertvector(v, bf16x2_t); return __builtin_bit_cast(unsigned, b); }
;     __device__ __forceinline__ void operator()(const f32x4 (&acc)[2][2][4][2], const Unit& u, int wr, int wc, int fr, int fq) const {
;     ...
;                 for (int ai = 0; ai < 2; ++ai)
; #pragma unroll
;                     for (int m = 0; m < 4; ++m) {
;                         const int row = row0 + ai * HALF + m * 16;
;                         const float rv = rsqrtf(rowss[row] * (1.0f / 1024.0f) + 1e-6f);
;                         const f32x4 v0 = (acc[ai][bj][m][0] * rv + bz0) * qsc, v1 = (acc[ai][bj][m][1] * rv + bz1) * qsc;
;                         if (isk) { float s2 = (v0[0] * v0[0] + v0[1] * v0[1]) + (v0[2] * v0[2] + v0[3] * v0[3]) + (v1[0] * v1[0] + v1[1] * v1[1]) + (v1[2] * v1[2] + v1[3] * v1[3]);
;                             s2 += __shfl_xor(s2, 16); s2 += __shfl_xor(s2, 32); kmx = fmaxf(kmx, s2); }
;                         u32x4 w; w.x = pk_bf16(v0[0], v0[1]); w.y = pk_bf16(v0[2], v0[3]); w.z = pk_bf16(v1[0], v1[1]); w.w = pk_bf16(v1[2], v1[3]);
;                         *(u32x4*)(base + (size_t)row * pitch) = w;
.LBB0_333:
	v_cvt_pk_bf16_f32 v41, v32, v33
	v_mad_i64_i32 v[32:33], s[0:1], s42, v241, 0
	v_cvt_pk_bf16_f32 v38, v38, v39
	v_cvt_pk_bf16_f32 v39, v36, v37
	v_cvt_pk_bf16_f32 v40, v34, v35
	v_lshl_add_u64 v[32:33], v[32:33], 1, v[56:57]
	global_store_dwordx4 v[32:33], v[38:41], off
	s_nop 0
	s_cmp_lt_i32 s66, 4
	v_fmamk_f32 v32, v197, 0x3a800000, v227
	v_cmp_gt_f32_e64 s[0:1], s36, v32
	s_cbranch_scc1 .LBB0_335
	s_cmp_eq_u32 s66, 4
	s_cselect_b64 s[4:5], -1, 0
	s_cbranch_execz .LBB0_336
	s_branch .LBB0_337

; __device__ __forceinline__ unsigned pk_bf16(float lo, float hi) { f32x2 v = {lo, hi}; bf16x2_t b = __builtin_convertvector(v, bf16x2_t); return __builtin_bit_cast(unsigned, b); }
;     __device__ __forceinline__ void operator()(const f32x4 (&acc)[2][2][4][2], const Unit& u, int wr, int wc, int fr, int fq) const {
;     ...
;                 for (int ai = 0; ai < 2; ++ai)
; #pragma unroll
;                     for (int m = 0; m < 4; ++m) {
;                         const int row = row0 + ai * HALF + m * 16;
;                         const float rv = rsqrtf(rowss[row] * (1.0f / 1024.0f) + 1e-6f);
;                         const f32x4 v0 = (acc[ai][bj][m][0] * rv + bz0) * qsc, v1 = (acc[ai][bj][m][1] * rv + bz1) * qsc;
;                         if (isk) { float s2 = (v0[0] * v0[0] + v0[1] * v0[1]) + (v0[2] * v0[2] + v0[3] * v0[3]) + (v1[0] * v1[0] + v1[1] * v1[1]) + (v1[2] * v1[2] + v1[3] * v1[3]);
;                             s2 += __shfl_xor(s2, 16); s2 += __shfl_xor(s2, 32); kmx = fmaxf(kmx, s2); }
;                         u32x4 w; w.x = pk_bf16(v0[0], v0[1]); w.y = pk_bf16(v0[2], v0[3]); w.z = pk_bf16(v1[0], v1[1]); w.w = pk_bf16(v1[2], v1[3]);
;                         *(u32x4*)(base + (size_t)row * pitch) = w;
.LBB0_339:
	v_cvt_pk_bf16_f32 v33, v24, v25
	v_mad_i64_i32 v[24:25], s[0:1], s42, v96, 0
	v_cvt_pk_bf16_f32 v30, v30, v31
	v_cvt_pk_bf16_f32 v31, v28, v29
	v_cvt_pk_bf16_f32 v32, v26, v27
	v_lshl_add_u64 v[24:25], v[24:25], 1, v[56:57]
	global_store_dwordx4 v[24:25], v[30:33], off
	s_nop 0
	s_cmp_lt_i32 s66, 4
	v_fmamk_f32 v24, v198, 0x3a800000, v227
	v_cmp_gt_f32_e64 s[0:1], s36, v24
	s_cbranch_scc1 .LBB0_341
	s_cmp_eq_u32 s66, 4
	s_cselect_b64 s[4:5], -1, 0
	s_cbranch_execz .LBB0_342
	s_branch .LBB0_343

; __device__ __forceinline__ unsigned pk_bf16(float lo, float hi) { f32x2 v = {lo, hi}; bf16x2_t b = __builtin_convertvector(v, bf16x2_t); return __builtin_bit_cast(unsigned, b); }
;     __device__ __forceinline__ void operator()(const f32x4 (&acc)[2][2][4][2], const Unit& u, int wr, int wc, int fr, int fq) const {
;     ...
;                 for (int ai = 0; ai < 2; ++ai)
; #pragma unroll
;                     for (int m = 0; m < 4; ++m) {
;                         const int row = row0 + ai * HALF + m * 16;
;                         const float rv = rsqrtf(rowss[row] * (1.0f / 1024.0f) + 1e-6f);
;                         const f32x4 v0 = (acc[ai][bj][m][0] * rv + bz0) * qsc, v1 = (acc[ai][bj][m][1] * rv + bz1) * qsc;
;                         if (isk) { float s2 = (v0[0] * v0[0] + v0[1] * v0[1]) + (v0[2] * v0[2] + v0[3] * v0[3]) + (v1[0] * v1[0] + v1[1] * v1[1]) + (v1[2] * v1[2] + v1[3] * v1[3]);
;                             s2 += __shfl_xor(s2, 16); s2 += __shfl_xor(s2, 32); kmx = fmaxf(kmx, s2); }
;                         u32x4 w; w.x = pk_bf16(v0[0], v0[1]); w.y = pk_bf16(v0[2], v0[3]); w.z = pk_bf16(v1[0], v1[1]); w.w = pk_bf16(v1[2], v1[3]);
;                         *(u32x4*)(base + (size_t)row * pitch) = w;
.LBB0_345:
	v_cvt_pk_bf16_f32 v25, v16, v17
	v_mad_i64_i32 v[16:17], s[0:1], s42, v90, 0
	v_cvt_pk_bf16_f32 v22, v22, v23
	v_cvt_pk_bf16_f32 v23, v20, v21
	v_cvt_pk_bf16_f32 v24, v18, v19
	v_lshl_add_u64 v[16:17], v[16:17], 1, v[56:57]
	global_store_dwordx4 v[16:17], v[22:25], off
	s_nop 0
	s_cmp_lt_i32 s66, 4
	v_fmamk_f32 v16, v199, 0x3a800000, v227
	v_cmp_gt_f32_e64 s[0:1], s36, v16
	s_cbranch_scc1 .LBB0_347
	s_cmp_eq_u32 s66, 4
	s_cselect_b64 s[4:5], -1, 0
	s_cbranch_execz .LBB0_348
	s_branch .LBB0_349

; __device__ __forceinline__ unsigned pk_bf16(float lo, float hi) { f32x2 v = {lo, hi}; bf16x2_t b = __builtin_convertvector(v, bf16x2_t); return __builtin_bit_cast(unsigned, b); }
;     __device__ __forceinline__ void operator()(const f32x4 (&acc)[2][2][4][2], const Unit& u, int wr, int wc, int fr, int fq) const {
;     ...
;                 for (int ai = 0; ai < 2; ++ai)
; #pragma unroll
;                     for (int m = 0; m < 4; ++m) {
;                         const int row = row0 + ai * HALF + m * 16;
;                         const float rv = rsqrtf(rowss[row] * (1.0f / 1024.0f) + 1e-6f);
;                         const f32x4 v0 = (acc[ai][bj][m][0] * rv + bz0) * qsc, v1 = (acc[ai][bj][m][1] * rv + bz1) * qsc;
;                         if (isk) { float s2 = (v0[0] * v0[0] + v0[1] * v0[1]) + (v0[2] * v0[2] + v0[3] * v0[3]) + (v1[0] * v1[0] + v1[1] * v1[1]) + (v1[2] * v1[2] + v1[3] * v1[3]);
;                             s2 += __shfl_xor(s2, 16); s2 += __shfl_xor(s2, 32); kmx = fmaxf(kmx, s2); }
;                         u32x4 w; w.x = pk_bf16(v0[0], v0[1]); w.y = pk_bf16(v0[2], v0[3]); w.z = pk_bf16(v1[0], v1[1]); w.w = pk_bf16(v1[2], v1[3]);
;                         *(u32x4*)(base + (size_t)row * pitch) = w;
.LBB0_351:
	v_cvt_pk_bf16_f32 v17, v8, v9
	v_mad_i64_i32 v[8:9], s[0:1], s42, v80, 0
	v_cvt_pk_bf16_f32 v14, v14, v15
	v_cvt_pk_bf16_f32 v15, v12, v13
	v_cvt_pk_bf16_f32 v16, v10, v11
	v_lshl_add_u64 v[8:9], v[8:9], 1, v[56:57]
	global_store_dwordx4 v[8:9], v[14:17], off
	s_nop 0
	s_cmp_lt_i32 s66, 4
	v_fmamk_f32 v8, v200, 0x3a800000, v227
	v_cmp_gt_f32_e64 s[0:1], s36, v8
	s_cbranch_scc1 .LBB0_353
	s_cmp_eq_u32 s66, 4
	s_cselect_b64 s[4:5], -1, 0
	s_cbranch_execz .LBB0_354
	s_branch .LBB0_355
